# key-norm task loop: all 32 row loads of a task issued together up front (were 8 serialized batches), counted waits per batch
# speedup vs baseline: 1.0094x; 1.0027x over previous
.LBB0_863:
	s_mul_hi_i32 s0, s23, 0x2aaaaaab
	s_lshr_b32 s1, s0, 31
	s_add_i32 s0, s0, s1
	v_lshl_add_u32 v17, s0, 11, v225
	s_mulk_i32 s0, 0xfe80
	v_readlane_b32 s40, v250, 15
	s_add_i32 s0, s2, s0
	v_readlane_b32 s54, v250, 29
	v_readlane_b32 s55, v250, 30
	s_ashr_i32 s1, s0, 31
	s_movk_i32 s10, 0x1080
	v_mov_b64_e32 v[12:13], s[54:55]
	s_waitcnt vmcnt(6)
	v_mad_i64_i32 v[0:1], s[4:5], v17, s10, v[12:13]
	s_lshl_b64 s[0:1], s[0:1], 1
	v_lshl_add_u64 v[0:1], v[0:1], 0, s[0:1]
	s_mov_b64 s[12:13], 0x4300300
	s_mov_b32 s11, 0x4300000
	v_lshl_add_u64 v[14:15], v[0:1], 0, s[12:13]
	v_add_co_u32_e32 v0, vcc, s11, v0
	v_readlane_b32 s41, v250, 16
	s_nop 0
	v_addc_co_u32_e32 v1, vcc, 0, v1, vcc
	v_mov_b32_e32 v34, 0x210000
	v_mov_b32_e32 v35, 0
	v_lshl_add_u64 v[28:29], v[14:15], 0, v[34:35]
	v_lshl_add_u64 v[30:31], v[28:29], 0, v[34:35]
	v_lshl_add_u64 v[32:33], v[30:31], 0, v[34:35]
	global_load_dwordx4 v[68:71], v[14:15], off
	global_load_dwordx4 v[72:75], v[14:15], off offset:48
	global_load_dwordx4 v[76:79], v[14:15], off offset:32
	global_load_dwordx4 v[80:83], v[14:15], off offset:16
	global_load_dwordx4 v[84:87], v[14:15], off offset:112
	global_load_dwordx4 v[88:91], v[14:15], off offset:96
	global_load_dwordx4 v[92:95], v[14:15], off offset:80
	global_load_dwordx4 v[96:99], v[14:15], off offset:64
	global_load_dwordx4 v[100:103], v[28:29], off
	global_load_dwordx4 v[104:107], v[28:29], off offset:48
	global_load_dwordx4 v[108:111], v[28:29], off offset:32
	global_load_dwordx4 v[112:115], v[28:29], off offset:16
	global_load_dwordx4 v[116:119], v[28:29], off offset:112
	global_load_dwordx4 v[120:123], v[28:29], off offset:96
	global_load_dwordx4 v[124:127], v[28:29], off offset:80
	global_load_dwordx4 v[128:131], v[28:29], off offset:64
	global_load_dwordx4 v[132:135], v[30:31], off
	global_load_dwordx4 v[136:139], v[30:31], off offset:48
	global_load_dwordx4 v[140:143], v[30:31], off offset:32
	global_load_dwordx4 v[144:147], v[30:31], off offset:16
	global_load_dwordx4 v[148:151], v[30:31], off offset:112
	global_load_dwordx4 v[152:155], v[30:31], off offset:96
	global_load_dwordx4 v[156:159], v[30:31], off offset:80
	global_load_dwordx4 v[160:163], v[30:31], off offset:64
	global_load_dwordx4 v[164:167], v[32:33], off
	global_load_dwordx4 v[168:171], v[32:33], off offset:48
	global_load_dwordx4 v[172:175], v[32:33], off offset:32
	global_load_dwordx4 v[176:179], v[32:33], off offset:16
	global_load_dwordx4 v[180:183], v[32:33], off offset:112
	global_load_dwordx4 v[184:187], v[32:33], off offset:96
	global_load_dwordx4 v[188:191], v[32:33], off offset:80
	global_load_dwordx4 v[192:195], v[32:33], off offset:64
	s_nop 0
	v_readlane_b32 s42, v250, 17
	v_readlane_b32 s43, v250, 18
	v_readlane_b32 s44, v250, 19
	v_readlane_b32 s45, v250, 20
	v_readlane_b32 s46, v250, 21
	v_readlane_b32 s47, v250, 22
	v_readlane_b32 s48, v250, 23
	v_readlane_b32 s49, v250, 24
	v_readlane_b32 s50, v250, 25
	v_readlane_b32 s51, v250, 26
	v_readlane_b32 s52, v250, 27
	v_readlane_b32 s53, v250, 28
	s_waitcnt vmcnt(31)
	v_lshlrev_b32_e32 v19, 16, v68
	v_and_b32_e32 v0, 0xffff0000, v68
	v_mul_f32_e32 v0, v0, v0
	v_lshlrev_b32_e32 v24, 16, v69
	v_fmac_f32_e32 v0, v19, v19
	v_and_b32_e32 v1, 0xffff0000, v69
	v_fmac_f32_e32 v0, v24, v24
	v_lshlrev_b32_e32 v25, 16, v70
	v_fmac_f32_e32 v0, v1, v1
	v_and_b32_e32 v2, 0xffff0000, v70
	v_fmac_f32_e32 v0, v25, v25
	v_lshlrev_b32_e32 v26, 16, v71
	v_fmac_f32_e32 v0, v2, v2
	s_waitcnt vmcnt(28)
	v_and_b32_e32 v2, 0xffff0000, v80
	v_and_b32_e32 v3, 0xffff0000, v71
	v_fmac_f32_e32 v0, v26, v26
	v_lshlrev_b32_e32 v1, 16, v80
	v_mul_f32_e32 v2, v2, v2
	v_fmac_f32_e32 v0, v3, v3
	v_lshlrev_b32_e32 v3, 16, v81
	v_fmac_f32_e32 v2, v1, v1
	v_and_b32_e32 v19, 0xffff0000, v81
	v_fmac_f32_e32 v2, v3, v3
	v_lshlrev_b32_e32 v20, 16, v82
	v_fmac_f32_e32 v2, v19, v19
	v_and_b32_e32 v21, 0xffff0000, v82
	v_fmac_f32_e32 v2, v20, v20
	v_lshlrev_b32_e32 v22, 16, v83
	v_fmac_f32_e32 v2, v21, v21
	v_and_b32_e32 v23, 0xffff0000, v83
	v_fmac_f32_e32 v2, v22, v22
	v_fmac_f32_e32 v2, v23, v23
	v_add_f32_e32 v0, v0, v2
	v_and_b32_e32 v2, 0xffff0000, v76
	v_lshlrev_b32_e32 v1, 16, v76
	v_mul_f32_e32 v2, v2, v2
	v_lshlrev_b32_e32 v3, 16, v77
	v_fmac_f32_e32 v2, v1, v1
	v_and_b32_e32 v8, 0xffff0000, v77
	v_fmac_f32_e32 v2, v3, v3
	v_lshlrev_b32_e32 v9, 16, v78
	v_fmac_f32_e32 v2, v8, v8
	v_and_b32_e32 v10, 0xffff0000, v78
	v_fmac_f32_e32 v2, v9, v9
	v_lshlrev_b32_e32 v19, 16, v79
	v_fmac_f32_e32 v2, v10, v10
	v_and_b32_e32 v11, 0xffff0000, v79
	v_fmac_f32_e32 v2, v19, v19
	v_fmac_f32_e32 v2, v11, v11
	v_add_f32_e32 v0, v0, v2
	v_and_b32_e32 v2, 0xffff0000, v72
	v_lshlrev_b32_e32 v1, 16, v72
	v_mul_f32_e32 v2, v2, v2
	v_lshlrev_b32_e32 v3, 16, v73
	v_fmac_f32_e32 v2, v1, v1
	v_and_b32_e32 v4, 0xffff0000, v73
	v_fmac_f32_e32 v2, v3, v3
	v_lshlrev_b32_e32 v5, 16, v74
	v_fmac_f32_e32 v2, v4, v4
	v_and_b32_e32 v6, 0xffff0000, v74
	v_fmac_f32_e32 v2, v5, v5
	v_lshlrev_b32_e32 v8, 16, v75
	v_fmac_f32_e32 v2, v6, v6
	v_and_b32_e32 v7, 0xffff0000, v75
	v_fmac_f32_e32 v2, v8, v8
	v_fmac_f32_e32 v2, v7, v7
	v_add_f32_e32 v19, v0, v2
	s_waitcnt vmcnt(24)
	v_and_b32_e32 v15, 0xffff0000, v96
	v_lshlrev_b32_e32 v14, 16, v96
	v_mul_f32_e32 v15, v15, v15
	v_fmac_f32_e32 v15, v14, v14
	v_lshlrev_b32_e32 v14, 16, v92
	v_and_b32_e32 v8, 0xffff0000, v92
	v_lshlrev_b32_e32 v20, 16, v97
	v_mul_f32_e32 v8, v8, v8
	v_fmac_f32_e32 v15, v20, v20
	v_lshlrev_b32_e32 v20, 16, v93
	v_fmac_f32_e32 v8, v14, v14
	v_and_b32_e32 v21, 0xffff0000, v97
	v_and_b32_e32 v9, 0xffff0000, v93
	v_fmac_f32_e32 v8, v20, v20
	v_lshlrev_b32_e32 v24, 16, v98
	v_fmac_f32_e32 v15, v21, v21
	v_lshlrev_b32_e32 v21, 16, v94
	v_fmac_f32_e32 v8, v9, v9
	v_lshlrev_b32_e32 v9, 16, v88
	v_and_b32_e32 v4, 0xffff0000, v88
	v_and_b32_e32 v22, 0xffff0000, v98
	v_fmac_f32_e32 v15, v24, v24
	v_and_b32_e32 v10, 0xffff0000, v94
	v_fmac_f32_e32 v8, v21, v21
	v_mul_f32_e32 v4, v4, v4
	v_fmac_f32_e32 v15, v22, v22
	v_lshlrev_b32_e32 v22, 16, v95
	v_fmac_f32_e32 v8, v10, v10
	v_lshlrev_b32_e32 v10, 16, v89
	v_fmac_f32_e32 v4, v9, v9
	v_and_b32_e32 v11, 0xffff0000, v95
	v_fmac_f32_e32 v8, v22, v22
	v_and_b32_e32 v5, 0xffff0000, v89
	v_fmac_f32_e32 v4, v10, v10
	v_fmac_f32_e32 v8, v11, v11
	v_lshlrev_b32_e32 v11, 16, v90
	v_fmac_f32_e32 v4, v5, v5
	v_lshlrev_b32_e32 v5, 16, v84
	v_and_b32_e32 v0, 0xffff0000, v84
	v_and_b32_e32 v6, 0xffff0000, v90
	v_fmac_f32_e32 v4, v11, v11
	v_mul_f32_e32 v0, v0, v0
	v_lshlrev_b32_e32 v25, 16, v99
	v_lshlrev_b32_e32 v14, 16, v91
	v_fmac_f32_e32 v4, v6, v6
	v_lshlrev_b32_e32 v6, 16, v85
	v_fmac_f32_e32 v0, v5, v5
	v_and_b32_e32 v23, 0xffff0000, v99
	v_fmac_f32_e32 v15, v25, v25
	v_and_b32_e32 v7, 0xffff0000, v91
	v_fmac_f32_e32 v4, v14, v14
	v_and_b32_e32 v1, 0xffff0000, v85
	v_fmac_f32_e32 v0, v6, v6
	v_fmac_f32_e32 v15, v23, v23
	v_fmac_f32_e32 v4, v7, v7
	v_lshlrev_b32_e32 v7, 16, v86
	v_fmac_f32_e32 v0, v1, v1
	v_add_f32_e32 v8, v15, v8
	v_and_b32_e32 v2, 0xffff0000, v86
	v_fmac_f32_e32 v0, v7, v7
	v_add_f32_e32 v4, v8, v4
	v_lshlrev_b32_e32 v8, 16, v87
	v_fmac_f32_e32 v0, v2, v2
	v_and_b32_e32 v3, 0xffff0000, v87
	v_fmac_f32_e32 v0, v8, v8
	v_fmac_f32_e32 v0, v3, v3
	v_add_f32_e32 v20, v4, v0
	v_add_u32_e32 v0, 0x200, v17
	v_mad_i64_i32 v[0:1], s[4:5], v0, s10, v[12:13]
	v_lshl_add_u64 v[0:1], v[0:1], 0, s[0:1]
	v_lshl_add_u64 v[14:15], v[0:1], 0, s[12:13]
	v_add_co_u32_e32 v0, vcc, s11, v0
	s_nop 1
	v_addc_co_u32_e32 v1, vcc, 0, v1, vcc
	s_nop 0
	s_waitcnt vmcnt(23)
	v_lshlrev_b32_e32 v21, 16, v100
	v_and_b32_e32 v4, 0xffff0000, v100
	v_mul_f32_e32 v4, v4, v4
	v_lshlrev_b32_e32 v26, 16, v101
	v_fmac_f32_e32 v4, v21, v21
	v_and_b32_e32 v5, 0xffff0000, v101
	v_fmac_f32_e32 v4, v26, v26
	v_lshlrev_b32_e32 v27, 16, v102
	v_fmac_f32_e32 v4, v5, v5
	v_and_b32_e32 v6, 0xffff0000, v102
	v_fmac_f32_e32 v4, v27, v27
	v_lshlrev_b32_e32 v28, 16, v103
	v_fmac_f32_e32 v4, v6, v6
	s_waitcnt vmcnt(20)
	v_and_b32_e32 v6, 0xffff0000, v112
	v_and_b32_e32 v7, 0xffff0000, v103
	v_fmac_f32_e32 v4, v28, v28
	v_lshlrev_b32_e32 v5, 16, v112
	v_mul_f32_e32 v6, v6, v6
	v_fmac_f32_e32 v4, v7, v7
	v_lshlrev_b32_e32 v7, 16, v113
	v_fmac_f32_e32 v6, v5, v5
	v_and_b32_e32 v21, 0xffff0000, v113
	v_fmac_f32_e32 v6, v7, v7
	v_lshlrev_b32_e32 v22, 16, v114
	v_fmac_f32_e32 v6, v21, v21
	v_and_b32_e32 v23, 0xffff0000, v114
	v_fmac_f32_e32 v6, v22, v22
	v_lshlrev_b32_e32 v24, 16, v115
	v_fmac_f32_e32 v6, v23, v23
	v_and_b32_e32 v25, 0xffff0000, v115
	v_fmac_f32_e32 v6, v24, v24
	v_fmac_f32_e32 v6, v25, v25
	v_add_f32_e32 v4, v4, v6
	v_and_b32_e32 v6, 0xffff0000, v108
	v_lshlrev_b32_e32 v5, 16, v108
	v_mul_f32_e32 v6, v6, v6
	v_lshlrev_b32_e32 v7, 16, v109
	v_fmac_f32_e32 v6, v5, v5
	v_and_b32_e32 v8, 0xffff0000, v109
	v_fmac_f32_e32 v6, v7, v7
	v_lshlrev_b32_e32 v9, 16, v110
	v_fmac_f32_e32 v6, v8, v8
	v_and_b32_e32 v10, 0xffff0000, v110
	v_fmac_f32_e32 v6, v9, v9
	v_lshlrev_b32_e32 v21, 16, v111
	v_fmac_f32_e32 v6, v10, v10
	v_and_b32_e32 v11, 0xffff0000, v111
	v_fmac_f32_e32 v6, v21, v21
	v_lshlrev_b32_e32 v5, 16, v104
	v_and_b32_e32 v0, 0xffff0000, v104
	v_fmac_f32_e32 v6, v11, v11
	v_mul_f32_e32 v0, v0, v0
	v_add_f32_e32 v4, v4, v6
	v_lshlrev_b32_e32 v6, 16, v105
	v_fmac_f32_e32 v0, v5, v5
	v_and_b32_e32 v1, 0xffff0000, v105
	v_fmac_f32_e32 v0, v6, v6
	v_lshlrev_b32_e32 v7, 16, v106
	v_fmac_f32_e32 v0, v1, v1
	v_and_b32_e32 v2, 0xffff0000, v106
	v_fmac_f32_e32 v0, v7, v7
	v_lshlrev_b32_e32 v8, 16, v107
	v_fmac_f32_e32 v0, v2, v2
	v_and_b32_e32 v3, 0xffff0000, v107
	v_fmac_f32_e32 v0, v8, v8
	v_fmac_f32_e32 v0, v3, v3
	v_add_f32_e32 v21, v4, v0
	v_max3_f32 v19, v19, 0, v21
	s_waitcnt vmcnt(16)
	v_and_b32_e32 v15, 0xffff0000, v128
	v_lshlrev_b32_e32 v14, 16, v128
	v_mul_f32_e32 v15, v15, v15
	v_fmac_f32_e32 v15, v14, v14
	v_lshlrev_b32_e32 v14, 16, v124
	v_and_b32_e32 v8, 0xffff0000, v124
	v_lshlrev_b32_e32 v22, 16, v129
	v_mul_f32_e32 v8, v8, v8
	v_fmac_f32_e32 v15, v22, v22
	v_lshlrev_b32_e32 v22, 16, v125
	v_fmac_f32_e32 v8, v14, v14
	v_and_b32_e32 v23, 0xffff0000, v129
	v_and_b32_e32 v9, 0xffff0000, v125
	v_fmac_f32_e32 v8, v22, v22
	v_lshlrev_b32_e32 v26, 16, v130
	v_fmac_f32_e32 v15, v23, v23
	v_lshlrev_b32_e32 v23, 16, v126
	v_fmac_f32_e32 v8, v9, v9
	v_lshlrev_b32_e32 v9, 16, v120
	v_and_b32_e32 v4, 0xffff0000, v120
	v_and_b32_e32 v24, 0xffff0000, v130
	v_fmac_f32_e32 v15, v26, v26
	v_and_b32_e32 v10, 0xffff0000, v126
	v_fmac_f32_e32 v8, v23, v23
	v_mul_f32_e32 v4, v4, v4
	v_fmac_f32_e32 v15, v24, v24
	v_lshlrev_b32_e32 v24, 16, v127
	v_fmac_f32_e32 v8, v10, v10
	v_lshlrev_b32_e32 v10, 16, v121
	v_fmac_f32_e32 v4, v9, v9
	v_and_b32_e32 v11, 0xffff0000, v127
	v_fmac_f32_e32 v8, v24, v24
	v_and_b32_e32 v5, 0xffff0000, v121
	v_fmac_f32_e32 v4, v10, v10
	v_fmac_f32_e32 v8, v11, v11
	v_lshlrev_b32_e32 v11, 16, v122
	v_fmac_f32_e32 v4, v5, v5
	v_lshlrev_b32_e32 v5, 16, v116
	v_and_b32_e32 v0, 0xffff0000, v116
	v_and_b32_e32 v6, 0xffff0000, v122
	v_fmac_f32_e32 v4, v11, v11
	v_mul_f32_e32 v0, v0, v0
	v_lshlrev_b32_e32 v27, 16, v131
	v_lshlrev_b32_e32 v14, 16, v123
	v_fmac_f32_e32 v4, v6, v6
	v_lshlrev_b32_e32 v6, 16, v117
	v_fmac_f32_e32 v0, v5, v5
	v_and_b32_e32 v25, 0xffff0000, v131
	v_fmac_f32_e32 v15, v27, v27
	v_and_b32_e32 v7, 0xffff0000, v123
	v_fmac_f32_e32 v4, v14, v14
	v_and_b32_e32 v1, 0xffff0000, v117
	v_fmac_f32_e32 v0, v6, v6
	v_fmac_f32_e32 v15, v25, v25
	v_fmac_f32_e32 v4, v7, v7
	v_lshlrev_b32_e32 v7, 16, v118
	v_fmac_f32_e32 v0, v1, v1
	v_add_f32_e32 v8, v15, v8
	v_and_b32_e32 v2, 0xffff0000, v118
	v_fmac_f32_e32 v0, v7, v7
	v_add_f32_e32 v4, v8, v4
	v_lshlrev_b32_e32 v8, 16, v119
	v_fmac_f32_e32 v0, v2, v2
	v_and_b32_e32 v3, 0xffff0000, v119
	v_fmac_f32_e32 v0, v8, v8
	v_fmac_f32_e32 v0, v3, v3
	v_add_f32_e32 v0, v4, v0
	v_max3_f32 v20, v20, 0, v0
	v_add_u32_e32 v0, 0x400, v17
	v_mad_i64_i32 v[0:1], s[4:5], v0, s10, v[12:13]
	v_lshl_add_u64 v[0:1], v[0:1], 0, s[0:1]
	v_lshl_add_u64 v[14:15], v[0:1], 0, s[12:13]
	v_add_co_u32_e32 v0, vcc, s11, v0
	s_nop 1
	v_addc_co_u32_e32 v1, vcc, 0, v1, vcc
	s_nop 0
	s_waitcnt vmcnt(15)
	v_lshlrev_b32_e32 v21, 16, v132
	v_and_b32_e32 v0, 0xffff0000, v132
	v_mul_f32_e32 v0, v0, v0
	v_lshlrev_b32_e32 v26, 16, v133
	v_fmac_f32_e32 v0, v21, v21
	v_and_b32_e32 v1, 0xffff0000, v133
	v_fmac_f32_e32 v0, v26, v26
	v_lshlrev_b32_e32 v27, 16, v134
	v_fmac_f32_e32 v0, v1, v1
	v_and_b32_e32 v2, 0xffff0000, v134
	v_fmac_f32_e32 v0, v27, v27
	v_lshlrev_b32_e32 v28, 16, v135
	v_fmac_f32_e32 v0, v2, v2
	s_waitcnt vmcnt(12)
	v_and_b32_e32 v2, 0xffff0000, v144
	v_and_b32_e32 v3, 0xffff0000, v135
	v_fmac_f32_e32 v0, v28, v28
	v_lshlrev_b32_e32 v1, 16, v144
	v_mul_f32_e32 v2, v2, v2
	v_fmac_f32_e32 v0, v3, v3
	v_lshlrev_b32_e32 v3, 16, v145
	v_fmac_f32_e32 v2, v1, v1
	v_and_b32_e32 v21, 0xffff0000, v145
	v_fmac_f32_e32 v2, v3, v3
	v_lshlrev_b32_e32 v22, 16, v146
	v_fmac_f32_e32 v2, v21, v21
	v_and_b32_e32 v23, 0xffff0000, v146
	v_fmac_f32_e32 v2, v22, v22
	v_lshlrev_b32_e32 v24, 16, v147
	v_fmac_f32_e32 v2, v23, v23
	v_and_b32_e32 v25, 0xffff0000, v147
	v_fmac_f32_e32 v2, v24, v24
	v_fmac_f32_e32 v2, v25, v25
	v_add_f32_e32 v0, v0, v2
	v_and_b32_e32 v2, 0xffff0000, v140
	v_lshlrev_b32_e32 v1, 16, v140
	v_mul_f32_e32 v2, v2, v2
	v_lshlrev_b32_e32 v3, 16, v141
	v_fmac_f32_e32 v2, v1, v1
	v_and_b32_e32 v8, 0xffff0000, v141
	v_fmac_f32_e32 v2, v3, v3
	v_lshlrev_b32_e32 v9, 16, v142
	v_fmac_f32_e32 v2, v8, v8
	v_and_b32_e32 v10, 0xffff0000, v142
	v_fmac_f32_e32 v2, v9, v9
	v_lshlrev_b32_e32 v21, 16, v143
	v_fmac_f32_e32 v2, v10, v10
	v_and_b32_e32 v11, 0xffff0000, v143
	v_fmac_f32_e32 v2, v21, v21
	v_fmac_f32_e32 v2, v11, v11
	v_add_f32_e32 v0, v0, v2
	v_and_b32_e32 v2, 0xffff0000, v136
	v_lshlrev_b32_e32 v1, 16, v136
	v_mul_f32_e32 v2, v2, v2
	v_lshlrev_b32_e32 v3, 16, v137
	v_fmac_f32_e32 v2, v1, v1
	v_and_b32_e32 v4, 0xffff0000, v137
	v_fmac_f32_e32 v2, v3, v3
	v_lshlrev_b32_e32 v5, 16, v138
	v_fmac_f32_e32 v2, v4, v4
	v_and_b32_e32 v6, 0xffff0000, v138
	v_fmac_f32_e32 v2, v5, v5
	v_lshlrev_b32_e32 v8, 16, v139
	v_fmac_f32_e32 v2, v6, v6
	v_and_b32_e32 v7, 0xffff0000, v139
	v_fmac_f32_e32 v2, v8, v8
	v_fmac_f32_e32 v2, v7, v7
	v_add_f32_e32 v21, v0, v2
	s_waitcnt vmcnt(8)
	v_and_b32_e32 v15, 0xffff0000, v160
	v_lshlrev_b32_e32 v14, 16, v160
	v_mul_f32_e32 v15, v15, v15
	v_fmac_f32_e32 v15, v14, v14
	v_lshlrev_b32_e32 v14, 16, v156
	v_and_b32_e32 v8, 0xffff0000, v156
	v_lshlrev_b32_e32 v22, 16, v161
	v_mul_f32_e32 v8, v8, v8
	v_fmac_f32_e32 v15, v22, v22
	v_lshlrev_b32_e32 v22, 16, v157
	v_fmac_f32_e32 v8, v14, v14
	v_and_b32_e32 v23, 0xffff0000, v161
	v_and_b32_e32 v9, 0xffff0000, v157
	v_fmac_f32_e32 v8, v22, v22
	v_lshlrev_b32_e32 v26, 16, v162
	v_fmac_f32_e32 v15, v23, v23
	v_lshlrev_b32_e32 v23, 16, v158
	v_fmac_f32_e32 v8, v9, v9
	v_lshlrev_b32_e32 v9, 16, v152
	v_and_b32_e32 v4, 0xffff0000, v152
	v_and_b32_e32 v24, 0xffff0000, v162
	v_fmac_f32_e32 v15, v26, v26
	v_and_b32_e32 v10, 0xffff0000, v158
	v_fmac_f32_e32 v8, v23, v23
	v_mul_f32_e32 v4, v4, v4
	v_fmac_f32_e32 v15, v24, v24
	v_lshlrev_b32_e32 v24, 16, v159
	v_fmac_f32_e32 v8, v10, v10
	v_lshlrev_b32_e32 v10, 16, v153
	v_fmac_f32_e32 v4, v9, v9
	v_and_b32_e32 v11, 0xffff0000, v159
	v_fmac_f32_e32 v8, v24, v24
	v_and_b32_e32 v5, 0xffff0000, v153
	v_fmac_f32_e32 v4, v10, v10
	v_fmac_f32_e32 v8, v11, v11
	v_lshlrev_b32_e32 v11, 16, v154
	v_fmac_f32_e32 v4, v5, v5
	v_lshlrev_b32_e32 v5, 16, v148
	v_and_b32_e32 v0, 0xffff0000, v148
	v_and_b32_e32 v6, 0xffff0000, v154
	v_fmac_f32_e32 v4, v11, v11
	v_mul_f32_e32 v0, v0, v0
	v_lshlrev_b32_e32 v27, 16, v163
	v_lshlrev_b32_e32 v14, 16, v155
	v_fmac_f32_e32 v4, v6, v6
	v_lshlrev_b32_e32 v6, 16, v149
	v_fmac_f32_e32 v0, v5, v5
	v_and_b32_e32 v25, 0xffff0000, v163
	v_fmac_f32_e32 v15, v27, v27
	v_and_b32_e32 v7, 0xffff0000, v155
	v_fmac_f32_e32 v4, v14, v14
	v_and_b32_e32 v1, 0xffff0000, v149
	v_fmac_f32_e32 v0, v6, v6
	v_fmac_f32_e32 v15, v25, v25
	v_fmac_f32_e32 v4, v7, v7
	v_lshlrev_b32_e32 v7, 16, v150
	v_fmac_f32_e32 v0, v1, v1
	v_add_f32_e32 v8, v15, v8
	v_and_b32_e32 v2, 0xffff0000, v150
	v_fmac_f32_e32 v0, v7, v7
	v_add_f32_e32 v4, v8, v4
	v_lshlrev_b32_e32 v8, 16, v151
	v_fmac_f32_e32 v0, v2, v2
	v_and_b32_e32 v3, 0xffff0000, v151
	v_fmac_f32_e32 v0, v8, v8
	v_fmac_f32_e32 v0, v3, v3
	v_add_f32_e32 v22, v4, v0
	v_add_u32_e32 v0, 0x600, v17
	v_mad_i64_i32 v[0:1], s[4:5], v0, s10, v[12:13]
	v_lshl_add_u64 v[0:1], v[0:1], 0, s[0:1]
	v_lshl_add_u64 v[12:13], v[0:1], 0, s[12:13]
	v_add_co_u32_e32 v0, vcc, s11, v0
	s_nop 1
	v_addc_co_u32_e32 v1, vcc, 0, v1, vcc
	s_nop 0
	s_waitcnt vmcnt(7)
	v_lshlrev_b32_e32 v14, 16, v164
	v_and_b32_e32 v0, 0xffff0000, v164
	v_mul_f32_e32 v0, v0, v0
	v_lshlrev_b32_e32 v15, 16, v165
	v_fmac_f32_e32 v0, v14, v14
	v_and_b32_e32 v1, 0xffff0000, v165
	v_fmac_f32_e32 v0, v15, v15
	v_lshlrev_b32_e32 v17, 16, v166
	v_fmac_f32_e32 v0, v1, v1
	v_and_b32_e32 v2, 0xffff0000, v166
	v_fmac_f32_e32 v0, v17, v17
	v_lshlrev_b32_e32 v23, 16, v167
	v_fmac_f32_e32 v0, v2, v2
	s_waitcnt vmcnt(4)
	v_and_b32_e32 v2, 0xffff0000, v176
	v_and_b32_e32 v3, 0xffff0000, v167
	v_fmac_f32_e32 v0, v23, v23
	v_lshlrev_b32_e32 v1, 16, v176
	v_mul_f32_e32 v2, v2, v2
	v_fmac_f32_e32 v0, v3, v3
	v_lshlrev_b32_e32 v3, 16, v177
	v_fmac_f32_e32 v2, v1, v1
	v_and_b32_e32 v14, 0xffff0000, v177
	v_fmac_f32_e32 v2, v3, v3
	v_lshlrev_b32_e32 v15, 16, v178
	v_fmac_f32_e32 v2, v14, v14
	v_and_b32_e32 v17, 0xffff0000, v178
	v_fmac_f32_e32 v2, v15, v15
	v_lshlrev_b32_e32 v23, 16, v179
	v_fmac_f32_e32 v2, v17, v17
	v_and_b32_e32 v24, 0xffff0000, v179
	v_fmac_f32_e32 v2, v23, v23
	v_fmac_f32_e32 v2, v24, v24
	v_add_f32_e32 v0, v0, v2
	v_and_b32_e32 v2, 0xffff0000, v172
	v_lshlrev_b32_e32 v1, 16, v172
	v_mul_f32_e32 v2, v2, v2
	v_lshlrev_b32_e32 v3, 16, v173
	v_fmac_f32_e32 v2, v1, v1
	v_and_b32_e32 v8, 0xffff0000, v173
	v_fmac_f32_e32 v2, v3, v3
	v_lshlrev_b32_e32 v9, 16, v174
	v_fmac_f32_e32 v2, v8, v8
	v_and_b32_e32 v10, 0xffff0000, v174
	v_fmac_f32_e32 v2, v9, v9
	v_lshlrev_b32_e32 v14, 16, v175
	v_fmac_f32_e32 v2, v10, v10
	v_and_b32_e32 v11, 0xffff0000, v175
	v_fmac_f32_e32 v2, v14, v14
	v_fmac_f32_e32 v2, v11, v11
	v_add_f32_e32 v0, v0, v2
	v_and_b32_e32 v2, 0xffff0000, v168
	v_lshlrev_b32_e32 v1, 16, v168
	v_mul_f32_e32 v2, v2, v2
	v_lshlrev_b32_e32 v3, 16, v169
	v_fmac_f32_e32 v2, v1, v1
	v_and_b32_e32 v4, 0xffff0000, v169
	v_fmac_f32_e32 v2, v3, v3
	v_lshlrev_b32_e32 v5, 16, v170
	v_fmac_f32_e32 v2, v4, v4
	v_and_b32_e32 v6, 0xffff0000, v170
	v_fmac_f32_e32 v2, v5, v5
	v_lshlrev_b32_e32 v8, 16, v171
	v_fmac_f32_e32 v2, v6, v6
	v_and_b32_e32 v7, 0xffff0000, v171
	v_fmac_f32_e32 v2, v8, v8
	v_fmac_f32_e32 v2, v7, v7
	v_add_f32_e32 v17, v0, v2
	s_nop 0
	s_barrier
	s_waitcnt vmcnt(0)
	v_lshlrev_b32_e32 v23, 16, v192
	v_and_b32_e32 v12, 0xffff0000, v192
	v_mul_f32_e32 v12, v12, v12
	v_lshlrev_b32_e32 v24, 16, v193
	v_fmac_f32_e32 v12, v23, v23
	v_and_b32_e32 v13, 0xffff0000, v193
	v_fmac_f32_e32 v12, v24, v24
	v_lshlrev_b32_e32 v25, 16, v194
	v_fmac_f32_e32 v12, v13, v13
	v_lshlrev_b32_e32 v13, 16, v188
	v_and_b32_e32 v8, 0xffff0000, v188
	v_and_b32_e32 v14, 0xffff0000, v194
	v_fmac_f32_e32 v12, v25, v25
	v_mul_f32_e32 v8, v8, v8
	v_lshlrev_b32_e32 v26, 16, v195
	v_fmac_f32_e32 v12, v14, v14
	v_lshlrev_b32_e32 v14, 16, v189
	v_fmac_f32_e32 v8, v13, v13
	v_and_b32_e32 v15, 0xffff0000, v195
	v_fmac_f32_e32 v12, v26, v26
	v_and_b32_e32 v9, 0xffff0000, v189
	v_fmac_f32_e32 v8, v14, v14
	v_fmac_f32_e32 v12, v15, v15
	v_lshlrev_b32_e32 v15, 16, v190
	v_fmac_f32_e32 v8, v9, v9
	v_lshlrev_b32_e32 v9, 16, v184
	v_and_b32_e32 v4, 0xffff0000, v184
	v_and_b32_e32 v10, 0xffff0000, v190
	v_fmac_f32_e32 v8, v15, v15
	v_mul_f32_e32 v4, v4, v4
	v_lshlrev_b32_e32 v23, 16, v191
	v_fmac_f32_e32 v8, v10, v10
	v_lshlrev_b32_e32 v10, 16, v185
	v_fmac_f32_e32 v4, v9, v9
	v_and_b32_e32 v11, 0xffff0000, v191
	v_fmac_f32_e32 v8, v23, v23
	v_and_b32_e32 v5, 0xffff0000, v185
	v_fmac_f32_e32 v4, v10, v10
	v_fmac_f32_e32 v8, v11, v11
	v_lshlrev_b32_e32 v11, 16, v186
	v_fmac_f32_e32 v4, v5, v5
	v_lshlrev_b32_e32 v5, 16, v180
	v_and_b32_e32 v0, 0xffff0000, v180
	v_and_b32_e32 v6, 0xffff0000, v186
	v_fmac_f32_e32 v4, v11, v11
	v_mul_f32_e32 v0, v0, v0
	v_add_f32_e32 v8, v12, v8
	v_lshlrev_b32_e32 v12, 16, v187
	v_fmac_f32_e32 v4, v6, v6
	v_lshlrev_b32_e32 v6, 16, v181
	v_fmac_f32_e32 v0, v5, v5
	v_and_b32_e32 v7, 0xffff0000, v187
	v_fmac_f32_e32 v4, v12, v12
	v_and_b32_e32 v1, 0xffff0000, v181
	v_fmac_f32_e32 v0, v6, v6
	v_fmac_f32_e32 v4, v7, v7
	v_lshlrev_b32_e32 v7, 16, v182
	v_fmac_f32_e32 v0, v1, v1
	v_and_b32_e32 v2, 0xffff0000, v182
	v_fmac_f32_e32 v0, v7, v7
	v_add_f32_e32 v4, v8, v4
	v_lshlrev_b32_e32 v8, 16, v183
	v_fmac_f32_e32 v0, v2, v2
	v_and_b32_e32 v3, 0xffff0000, v183
	v_fmac_f32_e32 v0, v8, v8
	v_fmac_f32_e32 v0, v3, v3
	v_add_f32_e32 v0, v4, v0
	v_max3_f32 v1, v19, v21, v17
	v_max3_f32 v2, v20, v22, v0
	ds_swizzle_b32 v0, v1 offset:swizzle(SWAP,1)
	ds_swizzle_b32 v3, v2 offset:swizzle(SWAP,1)
	s_waitcnt lgkmcnt(1)
	v_max_f32_e32 v0, v0, v0
	s_waitcnt lgkmcnt(0)
	v_max_f32_e32 v3, v3, v3
	v_max_f32_e32 v0, v1, v0
	v_max_f32_e32 v2, v2, v3
	ds_swizzle_b32 v1, v0 offset:swizzle(SWAP,2)
	ds_swizzle_b32 v3, v2 offset:swizzle(SWAP,2)
	s_waitcnt lgkmcnt(1)
	v_max_f32_e32 v1, v1, v1
	s_waitcnt lgkmcnt(0)
	v_max_f32_e32 v3, v3, v3
	v_max_f32_e32 v0, v0, v1
	v_max_f32_e32 v2, v2, v3
	ds_swizzle_b32 v1, v0 offset:swizzle(SWAP,4)
	ds_swizzle_b32 v3, v2 offset:swizzle(SWAP,4)
	s_waitcnt lgkmcnt(1)
	v_max_f32_e32 v1, v1, v1
	s_waitcnt lgkmcnt(0)
	v_max_f32_e32 v3, v3, v3
	v_max_f32_e32 v0, v0, v1
	v_max_f32_e32 v2, v2, v3
	ds_swizzle_b32 v1, v0 offset:swizzle(SWAP,8)
	ds_swizzle_b32 v3, v2 offset:swizzle(SWAP,8)
	s_waitcnt lgkmcnt(1)
	v_max_f32_e32 v1, v1, v1
	s_waitcnt lgkmcnt(0)
	v_max_f32_e32 v3, v3, v3
	v_max_f32_e32 v0, v0, v1
	v_max_f32_e32 v2, v2, v3
	ds_swizzle_b32 v1, v0 offset:swizzle(SWAP,16)
	ds_swizzle_b32 v3, v2 offset:swizzle(SWAP,16)
	s_waitcnt lgkmcnt(1)
	v_max_f32_e32 v1, v1, v1
	s_waitcnt lgkmcnt(0)
	v_max_f32_e32 v3, v3, v3
	v_max_f32_e32 v0, v0, v1
	v_max_f32_e32 v2, v2, v3
	v_mov_b32_e32 v1, v0
	v_mov_b32_e32 v3, v2
	s_nop 0
	v_permlane32_swap_b32_e32 v0, v1
	v_permlane32_swap_b32_e32 v2, v3
	s_and_saveexec_b64 s[0:1], s[6:7]
	s_cbranch_execz .LBB0_865
	v_max_f32_e32 v2, v2, v2
	v_max_f32_e32 v3, v3, v3
	v_max_f32_e32 v0, v0, v0
	v_max_f32_e32 v1, v1, v1
	v_readlane_b32 s4, v254, 51
	v_max_f32_e32 v3, v2, v3
	v_max_f32_e32 v2, v0, v1
	v_mov_b32_e32 v0, s4
	ds_write_b64 v0, v[2:3]
